# merge GEMM epilogue: first 12 of the 16 gate loads issued up front (own address arithmetic, idle registers), counted waits instead of load+store drains per granule
# baseline (speedup 1.0000x reference)
.LBB0_727:
	s_add_i32 s14, s14, 2
	s_add_u32 s40, s30, s12
	s_addc_u32 s41, s31, s13
	s_add_u32 s84, s26, s12
	s_addc_u32 s85, s27, s13
	s_add_i32 s86, 0, 0x10000
	ds_read_b128 v[134:137], v224
	ds_read_b128 v[152:155], v224 offset:1024
	ds_read_b128 v[162:165], v224 offset:2048
	ds_read_b128 v[166:169], v224 offset:3072
	s_cmp_eq_u32 s12, s22
	s_cselect_b32 s61, s51, s41
	s_cselect_b32 s60, s50, s40
	s_cselect_b32 s41, s49, s85
	s_cselect_b32 s40, s80, s84
	v_lshl_add_u64 v[202:203], v[132:133], 0, s[12:13]
	s_add_i32 m0, s66, 0xc000
	ds_read_b128 v[170:173], v160
	ds_read_b128 v[174:177], v160 offset:1024
	ds_read_b128 v[178:181], v160 offset:2048
	ds_read_b128 v[182:185], v160 offset:3072
	ds_read_b128 v[186:189], v160 offset:4096
	ds_read_b128 v[190:193], v160 offset:5120
	ds_read_b128 v[194:197], v160 offset:6144
	ds_read_b128 v[198:201], v160 offset:7168
	global_load_lds_dwordx4 v[202:203], off
	v_lshl_add_u64 v[202:203], v[130:131], 0, s[12:13]
	s_add_i32 m0, s66, 0xe000
	s_nop 0
	global_load_lds_dwordx4 v[202:203], off
	s_waitcnt lgkmcnt(8)
	s_barrier
	s_waitcnt lgkmcnt(7)
	v_mfma_f32_16x16x32_bf16 v[126:129], v[134:137], v[170:173], v[126:129]
	v_mfma_f32_16x16x32_bf16 v[122:125], v[162:165], v[170:173], v[122:125]
	s_waitcnt lgkmcnt(5)
	v_mfma_f32_16x16x32_bf16 v[110:113], v[134:137], v[178:181], v[110:113]
	v_mfma_f32_16x16x32_bf16 v[106:109], v[162:165], v[178:181], v[106:109]
	s_waitcnt lgkmcnt(3)
	v_mfma_f32_16x16x32_bf16 v[94:97], v[134:137], v[186:189], v[94:97]
	v_mfma_f32_16x16x32_bf16 v[90:93], v[162:165], v[186:189], v[90:93]
	s_waitcnt lgkmcnt(1)
	v_mfma_f32_16x16x32_bf16 v[78:81], v[134:137], v[194:197], v[78:81]
	v_mfma_f32_16x16x32_bf16 v[74:77], v[162:165], v[194:197], v[74:77]
	v_mfma_f32_16x16x32_bf16 v[126:129], v[152:155], v[174:177], v[126:129]
	v_mfma_f32_16x16x32_bf16 v[122:125], v[166:169], v[174:177], v[122:125]
	v_mfma_f32_16x16x32_bf16 v[110:113], v[152:155], v[182:185], v[110:113]
	v_mfma_f32_16x16x32_bf16 v[106:109], v[166:169], v[182:185], v[106:109]
	v_mfma_f32_16x16x32_bf16 v[94:97], v[152:155], v[190:193], v[94:97]
	v_mfma_f32_16x16x32_bf16 v[90:93], v[166:169], v[190:193], v[90:93]
	s_waitcnt lgkmcnt(0)
	v_mfma_f32_16x16x32_bf16 v[78:81], v[152:155], v[198:201], v[78:81]
	v_mfma_f32_16x16x32_bf16 v[74:77], v[166:169], v[198:201], v[74:77]
	s_barrier
	s_add_i32 s87, 0, 0x14000
	s_add_i32 s84, s86, s65
	s_mov_b32 m0, s84
	ds_read_b128 v[202:205], v225
	ds_read_b128 v[206:209], v225 offset:1024
	ds_read_b128 v[216:219], v225 offset:2048
	global_load_lds_dwordx4 v0, s[40:41]
	s_add_i32 m0, s84, 0x2000
	ds_read_b128 v[220:223], v225 offset:3072
	global_load_lds_dwordx4 v138, s[40:41]
	s_barrier
	s_waitcnt lgkmcnt(3)
	v_mfma_f32_16x16x32_bf16 v[118:121], v[202:205], v[170:173], v[118:121]
	s_waitcnt lgkmcnt(1)
	v_mfma_f32_16x16x32_bf16 v[114:117], v[216:219], v[170:173], v[114:117]
	v_mfma_f32_16x16x32_bf16 v[102:105], v[202:205], v[178:181], v[102:105]
	v_mfma_f32_16x16x32_bf16 v[98:101], v[216:219], v[178:181], v[98:101]
	v_mfma_f32_16x16x32_bf16 v[86:89], v[202:205], v[186:189], v[86:89]
	v_mfma_f32_16x16x32_bf16 v[82:85], v[216:219], v[186:189], v[82:85]
	v_mfma_f32_16x16x32_bf16 v[70:73], v[202:205], v[194:197], v[70:73]
	v_mfma_f32_16x16x32_bf16 v[66:69], v[216:219], v[194:197], v[66:69]
	v_mfma_f32_16x16x32_bf16 v[118:121], v[206:209], v[174:177], v[118:121]
	s_waitcnt lgkmcnt(0)
	v_mfma_f32_16x16x32_bf16 v[114:117], v[220:223], v[174:177], v[114:117]
	v_mfma_f32_16x16x32_bf16 v[102:105], v[206:209], v[182:185], v[102:105]
	v_mfma_f32_16x16x32_bf16 v[98:101], v[220:223], v[182:185], v[98:101]
	v_mfma_f32_16x16x32_bf16 v[86:89], v[206:209], v[190:193], v[86:89]
	v_mfma_f32_16x16x32_bf16 v[82:85], v[220:223], v[190:193], v[82:85]
	v_mfma_f32_16x16x32_bf16 v[70:73], v[206:209], v[198:201], v[70:73]
	v_mfma_f32_16x16x32_bf16 v[66:69], v[220:223], v[198:201], v[66:69]
	s_mov_b32 m0, s66
	s_add_u32 s98, s60, 0x80
	s_addc_u32 s99, s61, 0
	s_barrier
	ds_read_b128 v[170:173], v160 offset:16384
	ds_read_b128 v[174:177], v160 offset:17408
	ds_read_b128 v[178:181], v160 offset:18432
	ds_read_b128 v[182:185], v160 offset:19456
	ds_read_b128 v[186:189], v160 offset:20480
	ds_read_b128 v[190:193], v160 offset:21504
	ds_read_b128 v[194:197], v160 offset:22528
	global_load_lds_dwordx4 v142, s[60:61]
	s_mov_b32 m0, s67
	ds_read_b128 v[198:201], v160 offset:23552
	global_load_lds_dwordx4 v140, s[60:61]
	s_barrier
	s_waitcnt lgkmcnt(7)
	v_mfma_f32_16x16x32_bf16 v[62:65], v[134:137], v[170:173], v[62:65]
	v_mfma_f32_16x16x32_bf16 v[58:61], v[162:165], v[170:173], v[58:61]
	s_waitcnt lgkmcnt(5)
	v_mfma_f32_16x16x32_bf16 v[46:49], v[134:137], v[178:181], v[46:49]
	v_mfma_f32_16x16x32_bf16 v[42:45], v[162:165], v[178:181], v[42:45]
	s_waitcnt lgkmcnt(3)
	v_mfma_f32_16x16x32_bf16 v[30:33], v[134:137], v[186:189], v[30:33]
	v_mfma_f32_16x16x32_bf16 v[26:29], v[162:165], v[186:189], v[26:29]
	s_waitcnt lgkmcnt(1)
	v_mfma_f32_16x16x32_bf16 v[14:17], v[134:137], v[194:197], v[14:17]
	v_mfma_f32_16x16x32_bf16 v[10:13], v[162:165], v[194:197], v[10:13]
	v_mfma_f32_16x16x32_bf16 v[62:65], v[152:155], v[174:177], v[62:65]
	v_mfma_f32_16x16x32_bf16 v[58:61], v[166:169], v[174:177], v[58:61]
	v_mfma_f32_16x16x32_bf16 v[46:49], v[152:155], v[182:185], v[46:49]
	v_mfma_f32_16x16x32_bf16 v[42:45], v[166:169], v[182:185], v[42:45]
	v_mfma_f32_16x16x32_bf16 v[30:33], v[152:155], v[190:193], v[30:33]
	v_mfma_f32_16x16x32_bf16 v[26:29], v[166:169], v[190:193], v[26:29]
	s_waitcnt lgkmcnt(0)
	v_mfma_f32_16x16x32_bf16 v[14:17], v[152:155], v[198:201], v[14:17]
	v_mfma_f32_16x16x32_bf16 v[10:13], v[166:169], v[198:201], v[10:13]
	s_barrier
	s_add_i32 s86, s87, s65
	s_mov_b32 m0, s86
	s_add_u32 s84, s40, 0x100000
	s_addc_u32 s85, s41, 0
	global_load_lds_dwordx4 v0, s[84:85]
	s_add_i32 m0, s86, 0x2000
	s_nop 0
	global_load_lds_dwordx4 v138, s[84:85]
	s_waitcnt vmcnt(6)
	s_barrier
	v_mfma_f32_16x16x32_bf16 v[54:57], v[202:205], v[170:173], v[54:57]
	v_mfma_f32_16x16x32_bf16 v[50:53], v[216:219], v[170:173], v[50:53]
	v_mfma_f32_16x16x32_bf16 v[38:41], v[202:205], v[178:181], v[38:41]
	v_mfma_f32_16x16x32_bf16 v[34:37], v[216:219], v[178:181], v[34:37]
	v_mfma_f32_16x16x32_bf16 v[22:25], v[202:205], v[186:189], v[22:25]
	v_mfma_f32_16x16x32_bf16 v[18:21], v[216:219], v[186:189], v[18:21]
	v_mfma_f32_16x16x32_bf16 v[6:9], v[202:205], v[194:197], v[6:9]
	v_mfma_f32_16x16x32_bf16 v[2:5], v[216:219], v[194:197], v[2:5]
	v_mfma_f32_16x16x32_bf16 v[54:57], v[206:209], v[174:177], v[54:57]
	v_mfma_f32_16x16x32_bf16 v[50:53], v[220:223], v[174:177], v[50:53]
	v_mfma_f32_16x16x32_bf16 v[38:41], v[206:209], v[182:185], v[38:41]
	v_mfma_f32_16x16x32_bf16 v[34:37], v[220:223], v[182:185], v[34:37]
	v_mfma_f32_16x16x32_bf16 v[22:25], v[206:209], v[190:193], v[22:25]
	v_mfma_f32_16x16x32_bf16 v[18:21], v[220:223], v[190:193], v[18:21]
	v_mfma_f32_16x16x32_bf16 v[6:9], v[206:209], v[198:201], v[6:9]
	v_mfma_f32_16x16x32_bf16 v[2:5], v[220:223], v[198:201], v[2:5]
	s_add_i32 s84, 0, 0x18000
	s_barrier
	ds_read_b128 v[134:137], v226
	ds_read_b128 v[152:155], v226 offset:1024
	ds_read_b128 v[162:165], v226 offset:2048
	ds_read_b128 v[166:169], v226 offset:3072
	s_add_u32 s60, s60, 0x100000
	s_addc_u32 s61, s61, 0
	s_mov_b32 m0, s68
	ds_read_b128 v[170:173], v160 offset:32768
	ds_read_b128 v[174:177], v160 offset:33792
	ds_read_b128 v[178:181], v160 offset:34816
	ds_read_b128 v[182:185], v160 offset:35840
	ds_read_b128 v[186:189], v160 offset:36864
	ds_read_b128 v[190:193], v160 offset:37888
	ds_read_b128 v[194:197], v160 offset:38912
	global_load_lds_dwordx4 v142, s[60:61]
	s_mov_b32 m0, s69
	ds_read_b128 v[198:201], v160 offset:39936
	global_load_lds_dwordx4 v140, s[60:61]
	s_waitcnt lgkmcnt(8)
	s_barrier
	s_waitcnt lgkmcnt(7)
	v_mfma_f32_16x16x32_bf16 v[126:129], v[134:137], v[170:173], v[126:129]
	v_mfma_f32_16x16x32_bf16 v[122:125], v[162:165], v[170:173], v[122:125]
	s_waitcnt lgkmcnt(5)
	v_mfma_f32_16x16x32_bf16 v[110:113], v[134:137], v[178:181], v[110:113]
	v_mfma_f32_16x16x32_bf16 v[106:109], v[162:165], v[178:181], v[106:109]
	s_waitcnt lgkmcnt(3)
	v_mfma_f32_16x16x32_bf16 v[94:97], v[134:137], v[186:189], v[94:97]
	v_mfma_f32_16x16x32_bf16 v[90:93], v[162:165], v[186:189], v[90:93]
	s_waitcnt lgkmcnt(1)
	v_mfma_f32_16x16x32_bf16 v[78:81], v[134:137], v[194:197], v[78:81]
	v_mfma_f32_16x16x32_bf16 v[74:77], v[162:165], v[194:197], v[74:77]
	v_mfma_f32_16x16x32_bf16 v[126:129], v[152:155], v[174:177], v[126:129]
	v_mfma_f32_16x16x32_bf16 v[122:125], v[166:169], v[174:177], v[122:125]
	v_mfma_f32_16x16x32_bf16 v[110:113], v[152:155], v[182:185], v[110:113]
	v_mfma_f32_16x16x32_bf16 v[106:109], v[166:169], v[182:185], v[106:109]
	v_mfma_f32_16x16x32_bf16 v[94:97], v[152:155], v[190:193], v[94:97]
	v_mfma_f32_16x16x32_bf16 v[90:93], v[166:169], v[190:193], v[90:93]
	s_waitcnt lgkmcnt(0)
	v_mfma_f32_16x16x32_bf16 v[78:81], v[152:155], v[198:201], v[78:81]
	v_mfma_f32_16x16x32_bf16 v[74:77], v[166:169], v[198:201], v[74:77]
	s_barrier
	s_add_i32 s60, 0, 0x1c000
	s_add_i32 s61, s84, s65
	s_add_u32 s100, s40, 0x80
	s_addc_u32 s101, s41, 0
	s_mov_b32 m0, s61
	ds_read_b128 v[202:205], v227
	ds_read_b128 v[206:209], v227 offset:1024
	ds_read_b128 v[216:219], v227 offset:2048
	global_load_lds_dwordx4 v0, s[100:101]
	s_add_i32 m0, s61, 0x2000
	ds_read_b128 v[220:223], v227 offset:3072
	global_load_lds_dwordx4 v138, s[100:101]
	s_barrier
	s_waitcnt lgkmcnt(3)
	v_mfma_f32_16x16x32_bf16 v[118:121], v[202:205], v[170:173], v[118:121]
	s_waitcnt lgkmcnt(1)
	v_mfma_f32_16x16x32_bf16 v[114:117], v[216:219], v[170:173], v[114:117]
	v_mfma_f32_16x16x32_bf16 v[102:105], v[202:205], v[178:181], v[102:105]
	v_mfma_f32_16x16x32_bf16 v[98:101], v[216:219], v[178:181], v[98:101]
	v_mfma_f32_16x16x32_bf16 v[86:89], v[202:205], v[186:189], v[86:89]
	v_mfma_f32_16x16x32_bf16 v[82:85], v[216:219], v[186:189], v[82:85]
	v_mfma_f32_16x16x32_bf16 v[70:73], v[202:205], v[194:197], v[70:73]
	v_mfma_f32_16x16x32_bf16 v[66:69], v[216:219], v[194:197], v[66:69]
	v_mfma_f32_16x16x32_bf16 v[118:121], v[206:209], v[174:177], v[118:121]
	s_waitcnt lgkmcnt(0)
	v_mfma_f32_16x16x32_bf16 v[114:117], v[220:223], v[174:177], v[114:117]
	v_mfma_f32_16x16x32_bf16 v[102:105], v[206:209], v[182:185], v[102:105]
	v_mfma_f32_16x16x32_bf16 v[98:101], v[220:223], v[182:185], v[98:101]
	v_mfma_f32_16x16x32_bf16 v[86:89], v[206:209], v[190:193], v[86:89]
	v_mfma_f32_16x16x32_bf16 v[82:85], v[220:223], v[190:193], v[82:85]
	v_mfma_f32_16x16x32_bf16 v[70:73], v[206:209], v[198:201], v[70:73]
	v_mfma_f32_16x16x32_bf16 v[66:69], v[220:223], v[198:201], v[66:69]
	s_mov_b32 m0, s76
	s_barrier
	ds_read_b128 v[170:173], v160 offset:49152
	ds_read_b128 v[174:177], v160 offset:50176
	ds_read_b128 v[178:181], v160 offset:51200
	ds_read_b128 v[182:185], v160 offset:52224
	ds_read_b128 v[186:189], v160 offset:53248
	ds_read_b128 v[190:193], v160 offset:54272
	ds_read_b128 v[194:197], v160 offset:55296
	global_load_lds_dwordx4 v142, s[98:99]
	s_mov_b32 m0, s77
	ds_read_b128 v[198:201], v160 offset:56320
	global_load_lds_dwordx4 v140, s[98:99]
	s_barrier
	s_waitcnt lgkmcnt(7)
	v_mfma_f32_16x16x32_bf16 v[62:65], v[134:137], v[170:173], v[62:65]
	v_mfma_f32_16x16x32_bf16 v[58:61], v[162:165], v[170:173], v[58:61]
	s_waitcnt lgkmcnt(5)
	v_mfma_f32_16x16x32_bf16 v[46:49], v[134:137], v[178:181], v[46:49]
	v_mfma_f32_16x16x32_bf16 v[42:45], v[162:165], v[178:181], v[42:45]
	s_waitcnt lgkmcnt(3)
	v_mfma_f32_16x16x32_bf16 v[30:33], v[134:137], v[186:189], v[30:33]
	v_mfma_f32_16x16x32_bf16 v[26:29], v[162:165], v[186:189], v[26:29]
	s_waitcnt lgkmcnt(1)
	v_mfma_f32_16x16x32_bf16 v[14:17], v[134:137], v[194:197], v[14:17]
	v_mfma_f32_16x16x32_bf16 v[10:13], v[162:165], v[194:197], v[10:13]
	v_mfma_f32_16x16x32_bf16 v[62:65], v[152:155], v[174:177], v[62:65]
	v_mfma_f32_16x16x32_bf16 v[58:61], v[166:169], v[174:177], v[58:61]
	v_mfma_f32_16x16x32_bf16 v[46:49], v[152:155], v[182:185], v[46:49]
	v_mfma_f32_16x16x32_bf16 v[42:45], v[166:169], v[182:185], v[42:45]
	v_mfma_f32_16x16x32_bf16 v[30:33], v[152:155], v[190:193], v[30:33]
	v_mfma_f32_16x16x32_bf16 v[26:29], v[166:169], v[190:193], v[26:29]
	s_waitcnt lgkmcnt(0)
	v_mfma_f32_16x16x32_bf16 v[14:17], v[152:155], v[198:201], v[14:17]
	v_mfma_f32_16x16x32_bf16 v[10:13], v[166:169], v[198:201], v[10:13]
	s_barrier
	s_add_i32 s60, s60, s65
	s_mov_b32 m0, s60
	s_add_u32 s40, s40, 0x100080
	s_addc_u32 s41, s41, 0
	global_load_lds_dwordx4 v0, s[40:41]
	s_add_i32 m0, s60, 0x2000
	s_nop 0
	global_load_lds_dwordx4 v138, s[40:41]
	s_waitcnt vmcnt(6)
	s_barrier
	v_mfma_f32_16x16x32_bf16 v[54:57], v[202:205], v[170:173], v[54:57]
	v_mfma_f32_16x16x32_bf16 v[50:53], v[216:219], v[170:173], v[50:53]
	v_mfma_f32_16x16x32_bf16 v[38:41], v[202:205], v[178:181], v[38:41]
	v_mfma_f32_16x16x32_bf16 v[34:37], v[216:219], v[178:181], v[34:37]
	v_mfma_f32_16x16x32_bf16 v[22:25], v[202:205], v[186:189], v[22:25]
	v_mfma_f32_16x16x32_bf16 v[18:21], v[216:219], v[186:189], v[18:21]
	v_mfma_f32_16x16x32_bf16 v[6:9], v[202:205], v[194:197], v[6:9]
	v_mfma_f32_16x16x32_bf16 v[2:5], v[216:219], v[194:197], v[2:5]
	v_mfma_f32_16x16x32_bf16 v[54:57], v[206:209], v[174:177], v[54:57]
	v_mfma_f32_16x16x32_bf16 v[50:53], v[220:223], v[174:177], v[50:53]
	v_mfma_f32_16x16x32_bf16 v[38:41], v[206:209], v[182:185], v[38:41]
	v_mfma_f32_16x16x32_bf16 v[34:37], v[220:223], v[182:185], v[34:37]
	v_mfma_f32_16x16x32_bf16 v[22:25], v[206:209], v[190:193], v[22:25]
	v_mfma_f32_16x16x32_bf16 v[18:21], v[220:223], v[190:193], v[18:21]
	v_mfma_f32_16x16x32_bf16 v[6:9], v[206:209], v[198:201], v[6:9]
	v_mfma_f32_16x16x32_bf16 v[2:5], v[220:223], v[198:201], v[2:5]
	s_add_u32 s30, s30, 0x100
	s_addc_u32 s31, s31, 0
	s_add_u32 s26, s26, 0x100
	s_addc_u32 s27, s27, 0
	s_add_u32 s22, s22, 0xffffff00
	s_addc_u32 s23, s23, -1
	v_lshl_add_u64 v[132:133], v[132:133], 0, s[18:19]
	s_cmp_ge_u32 s14, vcc_lo
	v_lshl_add_u64 v[130:131], v[130:131], 0, s[18:19]
	s_barrier
	s_cbranch_scc0 .LBB0_727
	s_mov_b32 s14, 32
	s_mov_b64 s[26:27], 0
	s_andn2_b64 vcc, exec, s[6:7]
	s_mov_b64 s[6:7], -1
	s_cbranch_vccnz .LBB0_724
	v_mov_b32_e32 v130, v148
	v_mov_b64_e32 v[134:135], s[38:39]
	v_and_or_b32 v132, v130, 15, s82
	v_lshrrev_b32_e32 v130, 1, v130
	v_and_or_b32 v130, v130, 24, s75
	v_or_b32_e32 v130, s81, v130
	s_mov_b32 s14, s48
	v_ashrrev_i32_e32 v131, 31, v130
	v_mad_i64_i32 v[136:137], s[0:1], v132, s47, v[134:135]
	v_lshlrev_b64 v[130:131], 1, v[130:131]
	v_lshl_add_u64 v[136:137], v[136:137], 0, v[130:131]
	v_add_co_u32_e32 v152, vcc, s72, v136
	v_ashrrev_i32_e32 v133, 31, v132
	s_nop 0
	v_addc_co_u32_e32 v153, vcc, 0, v137, vcc
	v_add_co_u32_e32 v206, vcc, s72, v136
	s_nop 1
	v_addc_co_u32_e32 v207, vcc, 0, v137, vcc
	global_load_dwordx4 v[164:167], v[206:207], off
	v_lshl_add_u64 v[208:209], v[136:137], 0, s[34:35]
	global_load_dwordx4 v[168:171], v[208:209], off offset:256
	v_add_u32_e32 v206, 16, v132
	v_mad_i64_i32 v[204:205], s[0:1], v206, s47, v[134:135]
	v_lshl_add_u64 v[204:205], v[204:205], 0, v[130:131]
	v_add_co_u32_e32 v206, vcc, s72, v204
	s_nop 1
	v_addc_co_u32_e32 v207, vcc, 0, v205, vcc
	global_load_dwordx4 v[172:175], v[206:207], off
	v_lshl_add_u64 v[208:209], v[204:205], 0, s[34:35]
	global_load_dwordx4 v[176:179], v[208:209], off offset:256
	v_add_u32_e32 v206, 32, v132
	v_mad_i64_i32 v[204:205], s[0:1], v206, s47, v[134:135]
	v_lshl_add_u64 v[204:205], v[204:205], 0, v[130:131]
	v_add_co_u32_e32 v206, vcc, s72, v204
	s_nop 1
	v_addc_co_u32_e32 v207, vcc, 0, v205, vcc
	global_load_dwordx4 v[180:183], v[206:207], off
	v_lshl_add_u64 v[208:209], v[204:205], 0, s[34:35]
	global_load_dwordx4 v[184:187], v[208:209], off offset:256
	v_add_u32_e32 v206, 48, v132
	v_mad_i64_i32 v[204:205], s[0:1], v206, s47, v[134:135]
	v_lshl_add_u64 v[204:205], v[204:205], 0, v[130:131]
	v_add_co_u32_e32 v206, vcc, s72, v204
	s_nop 1
	v_addc_co_u32_e32 v207, vcc, 0, v205, vcc
	global_load_dwordx4 v[188:191], v[206:207], off
	v_lshl_add_u64 v[208:209], v[204:205], 0, s[34:35]
	global_load_dwordx4 v[192:195], v[208:209], off offset:256
	v_add_u32_e32 v206, 128, v132
	v_mad_i64_i32 v[204:205], s[0:1], v206, s47, v[134:135]
	v_lshl_add_u64 v[204:205], v[204:205], 0, v[130:131]
	v_add_co_u32_e32 v206, vcc, s72, v204
	s_nop 1
	v_addc_co_u32_e32 v207, vcc, 0, v205, vcc
	global_load_dwordx4 v[196:199], v[206:207], off
	v_lshl_add_u64 v[208:209], v[204:205], 0, s[34:35]
	global_load_dwordx4 v[200:203], v[208:209], off offset:256
	v_add_u32_e32 v206, 144, v132
	v_mad_i64_i32 v[204:205], s[0:1], v206, s47, v[134:135]
	v_lshl_add_u64 v[204:205], v[204:205], 0, v[130:131]
	v_add_co_u32_e32 v206, vcc, s72, v204
	s_nop 1
	v_addc_co_u32_e32 v207, vcc, 0, v205, vcc
	global_load_dwordx4 v[216:219], v[206:207], off
	v_lshl_add_u64 v[208:209], v[204:205], 0, s[34:35]
	global_load_dwordx4 v[220:223], v[208:209], off offset:256
	v_lshlrev_b64 v[156:157], 12, v[132:133]
	v_lshl_add_u64 v[156:157], s[28:29], 0, v[156:157]
	v_lshl_add_u64 v[156:157], v[156:157], 0, v[130:131]
	v_lshl_add_u64 v[136:137], v[136:137], 0, s[34:35]
	s_mov_b32 s22, s79
	s_mov_b64 s[6:7], s[52:53]
	s_mov_b64 s[12:13], s[50:51]
	s_waitcnt vmcnt(11)
	v_lshlrev_b32_e32 v158, 16, v164
	v_and_b32_e32 v159, 0xffff0000, v164
	v_lshlrev_b32_e32 v152, 16, v165
	v_and_b32_e32 v153, 0xffff0000, v165
	v_lshlrev_b32_e32 v162, 16, v166
	v_and_b32_e32 v163, 0xffff0000, v166
	v_lshlrev_b32_e32 v154, 16, v167
	v_and_b32_e32 v155, 0xffff0000, v167
	v_pk_mul_f32 v[128:129], v[128:129], v[152:153]
	v_pk_mul_f32 v[126:127], v[126:127], v[158:159]
	v_pk_mul_f32 v[152:153], v[124:125], v[154:155]
	v_pk_mul_f32 v[124:125], v[122:123], v[162:163]
	v_cvt_pk_bf16_f32 v122, v126, v127
	v_cvt_pk_bf16_f32 v123, v128, v129
	v_cvt_pk_bf16_f32 v124, v124, v125
	v_cvt_pk_bf16_f32 v125, v152, v153
	global_store_dwordx4 v[156:157], v[122:125], off

	v_add_u32_e32 v126, 16, v132
	v_mad_i64_i32 v[128:129], s[0:1], v126, s47, v[134:135]
	v_lshl_add_u64 v[128:129], v[128:129], 0, v[130:131]
	v_add_co_u32_e32 v136, vcc, s72, v128
	v_ashrrev_i32_e32 v127, 31, v126
	s_nop 0
	v_addc_co_u32_e32 v137, vcc, 0, v129, vcc
	s_waitcnt vmcnt(11)
	v_lshlrev_b32_e32 v152, 16, v168
	v_and_b32_e32 v153, 0xffff0000, v168
	v_lshlrev_b32_e32 v122, 16, v169
	v_and_b32_e32 v123, 0xffff0000, v169
	v_lshlrev_b32_e32 v154, 16, v170
	v_and_b32_e32 v155, 0xffff0000, v170
	v_lshlrev_b32_e32 v124, 16, v171
	v_and_b32_e32 v125, 0xffff0000, v171
	v_pk_mul_f32 v[120:121], v[120:121], v[122:123]
	v_pk_mul_f32 v[118:119], v[118:119], v[152:153]
	v_pk_mul_f32 v[122:123], v[116:117], v[124:125]
	v_pk_mul_f32 v[116:117], v[114:115], v[154:155]
	v_cvt_pk_bf16_f32 v114, v118, v119
	v_cvt_pk_bf16_f32 v115, v120, v121
	v_cvt_pk_bf16_f32 v116, v116, v117
	v_cvt_pk_bf16_f32 v117, v122, v123
	global_store_dwordx4 v[156:157], v[114:117], off offset:256

	v_lshlrev_b64 v[118:119], 12, v[126:127]
	v_lshl_add_u64 v[118:119], s[28:29], 0, v[118:119]
	v_lshl_add_u64 v[118:119], v[118:119], 0, v[130:131]
	v_lshl_add_u64 v[120:121], v[128:129], 0, s[34:35]
	s_waitcnt vmcnt(11)
	v_lshlrev_b32_e32 v122, 16, v172
	v_and_b32_e32 v123, 0xffff0000, v172
	v_lshlrev_b32_e32 v114, 16, v173
	v_and_b32_e32 v115, 0xffff0000, v173
	v_lshlrev_b32_e32 v124, 16, v174
	v_and_b32_e32 v125, 0xffff0000, v174
	v_lshlrev_b32_e32 v116, 16, v175
	v_and_b32_e32 v117, 0xffff0000, v175
	v_pk_mul_f32 v[112:113], v[112:113], v[114:115]
	v_pk_mul_f32 v[110:111], v[110:111], v[122:123]
	v_pk_mul_f32 v[114:115], v[108:109], v[116:117]
	v_pk_mul_f32 v[108:109], v[106:107], v[124:125]
	v_cvt_pk_bf16_f32 v106, v110, v111
	v_cvt_pk_bf16_f32 v107, v112, v113
	v_cvt_pk_bf16_f32 v108, v108, v109
	v_cvt_pk_bf16_f32 v109, v114, v115
	global_store_dwordx4 v[118:119], v[106:109], off

	v_add_u32_e32 v110, 32, v132
	v_mad_i64_i32 v[112:113], s[0:1], v110, s47, v[134:135]
	v_lshl_add_u64 v[112:113], v[112:113], 0, v[130:131]
	v_add_co_u32_e32 v114, vcc, s72, v112
	v_ashrrev_i32_e32 v111, 31, v110
	s_nop 0
	v_addc_co_u32_e32 v115, vcc, 0, v113, vcc
	s_waitcnt vmcnt(11)
	v_lshlrev_b32_e32 v116, 16, v176
	v_and_b32_e32 v117, 0xffff0000, v176
	v_lshlrev_b32_e32 v106, 16, v177
	v_and_b32_e32 v107, 0xffff0000, v177
	v_lshlrev_b32_e32 v120, 16, v178
	v_and_b32_e32 v121, 0xffff0000, v178
	v_lshlrev_b32_e32 v108, 16, v179
	v_and_b32_e32 v109, 0xffff0000, v179
	v_pk_mul_f32 v[104:105], v[104:105], v[106:107]
	v_pk_mul_f32 v[102:103], v[102:103], v[116:117]
	v_pk_mul_f32 v[106:107], v[100:101], v[108:109]
	v_pk_mul_f32 v[100:101], v[98:99], v[120:121]
	v_cvt_pk_bf16_f32 v98, v102, v103
	v_cvt_pk_bf16_f32 v99, v104, v105
	v_cvt_pk_bf16_f32 v100, v100, v101
	v_cvt_pk_bf16_f32 v101, v106, v107
	global_store_dwordx4 v[118:119], v[98:101], off offset:256

	v_lshlrev_b64 v[102:103], 12, v[110:111]
	v_lshl_add_u64 v[102:103], s[28:29], 0, v[102:103]
	v_lshl_add_u64 v[102:103], v[102:103], 0, v[130:131]
	v_lshl_add_u64 v[104:105], v[112:113], 0, s[34:35]
	s_waitcnt vmcnt(11)
	v_lshlrev_b32_e32 v106, 16, v180
	v_and_b32_e32 v107, 0xffff0000, v180
	v_lshlrev_b32_e32 v98, 16, v181
	v_and_b32_e32 v99, 0xffff0000, v181
	v_lshlrev_b32_e32 v108, 16, v182
	v_and_b32_e32 v109, 0xffff0000, v182
	v_lshlrev_b32_e32 v100, 16, v183
	v_and_b32_e32 v101, 0xffff0000, v183
	v_pk_mul_f32 v[96:97], v[96:97], v[98:99]
	v_pk_mul_f32 v[94:95], v[94:95], v[106:107]
	v_pk_mul_f32 v[98:99], v[92:93], v[100:101]
	v_pk_mul_f32 v[92:93], v[90:91], v[108:109]
	v_cvt_pk_bf16_f32 v90, v94, v95
	v_cvt_pk_bf16_f32 v91, v96, v97
	v_cvt_pk_bf16_f32 v92, v92, v93
	v_cvt_pk_bf16_f32 v93, v98, v99
	global_store_dwordx4 v[102:103], v[90:93], off

	v_add_u32_e32 v94, 48, v132
	v_mad_i64_i32 v[96:97], s[0:1], v94, s47, v[134:135]
	v_lshl_add_u64 v[96:97], v[96:97], 0, v[130:131]
	v_add_co_u32_e32 v98, vcc, s72, v96
	v_ashrrev_i32_e32 v95, 31, v94
	s_nop 0
	v_addc_co_u32_e32 v99, vcc, 0, v97, vcc
	s_waitcnt vmcnt(11)
	v_lshlrev_b32_e32 v100, 16, v184
	v_and_b32_e32 v101, 0xffff0000, v184
	v_lshlrev_b32_e32 v90, 16, v185
	v_and_b32_e32 v91, 0xffff0000, v185
	v_lshlrev_b32_e32 v104, 16, v186
	v_and_b32_e32 v105, 0xffff0000, v186
	v_lshlrev_b32_e32 v92, 16, v187
	v_and_b32_e32 v93, 0xffff0000, v187
	v_pk_mul_f32 v[88:89], v[88:89], v[90:91]
	v_pk_mul_f32 v[86:87], v[86:87], v[100:101]
	v_pk_mul_f32 v[90:91], v[84:85], v[92:93]
	v_pk_mul_f32 v[84:85], v[82:83], v[104:105]
	v_cvt_pk_bf16_f32 v82, v86, v87
	v_cvt_pk_bf16_f32 v83, v88, v89
	v_cvt_pk_bf16_f32 v84, v84, v85
	v_cvt_pk_bf16_f32 v85, v90, v91
	global_store_dwordx4 v[102:103], v[82:85], off offset:256

	v_lshlrev_b64 v[86:87], 12, v[94:95]
	v_lshl_add_u64 v[86:87], s[28:29], 0, v[86:87]
	v_lshl_add_u64 v[86:87], v[86:87], 0, v[130:131]
	v_lshl_add_u64 v[88:89], v[96:97], 0, s[34:35]
	s_waitcnt vmcnt(11)
	v_lshlrev_b32_e32 v90, 16, v188
	v_and_b32_e32 v91, 0xffff0000, v188
	v_lshlrev_b32_e32 v82, 16, v189
	v_and_b32_e32 v83, 0xffff0000, v189
	v_lshlrev_b32_e32 v92, 16, v190
	v_and_b32_e32 v93, 0xffff0000, v190
	v_lshlrev_b32_e32 v84, 16, v191
	v_and_b32_e32 v85, 0xffff0000, v191
	v_pk_mul_f32 v[80:81], v[80:81], v[82:83]
	v_pk_mul_f32 v[78:79], v[78:79], v[90:91]
	v_pk_mul_f32 v[82:83], v[76:77], v[84:85]
	v_pk_mul_f32 v[76:77], v[74:75], v[92:93]
	v_cvt_pk_bf16_f32 v74, v78, v79
	v_cvt_pk_bf16_f32 v75, v80, v81
	v_cvt_pk_bf16_f32 v76, v76, v77
	v_cvt_pk_bf16_f32 v77, v82, v83
	global_store_dwordx4 v[86:87], v[74:77], off

	v_add_u32_e32 v78, 0x80, v132
	v_mad_i64_i32 v[80:81], s[0:1], v78, s47, v[134:135]
	v_lshl_add_u64 v[80:81], v[80:81], 0, v[130:131]
	v_add_co_u32_e32 v82, vcc, s72, v80
	v_ashrrev_i32_e32 v79, 31, v78
	s_nop 0
	v_addc_co_u32_e32 v83, vcc, 0, v81, vcc
	s_waitcnt vmcnt(11)
	v_lshlrev_b32_e32 v84, 16, v192
	v_and_b32_e32 v85, 0xffff0000, v192
	v_lshlrev_b32_e32 v74, 16, v193
	v_and_b32_e32 v75, 0xffff0000, v193
	v_lshlrev_b32_e32 v88, 16, v194
	v_and_b32_e32 v89, 0xffff0000, v194
	v_lshlrev_b32_e32 v76, 16, v195
	v_and_b32_e32 v77, 0xffff0000, v195
	v_pk_mul_f32 v[72:73], v[72:73], v[74:75]
	v_pk_mul_f32 v[70:71], v[70:71], v[84:85]
	v_pk_mul_f32 v[74:75], v[68:69], v[76:77]
	v_pk_mul_f32 v[68:69], v[66:67], v[88:89]
	v_cvt_pk_bf16_f32 v66, v70, v71
	v_cvt_pk_bf16_f32 v67, v72, v73
	v_cvt_pk_bf16_f32 v68, v68, v69
	v_cvt_pk_bf16_f32 v69, v74, v75
	global_store_dwordx4 v[86:87], v[66:69], off offset:256

	v_lshlrev_b64 v[70:71], 12, v[78:79]
	v_lshl_add_u64 v[70:71], s[28:29], 0, v[70:71]
	v_lshl_add_u64 v[70:71], v[70:71], 0, v[130:131]
	v_lshl_add_u64 v[72:73], v[80:81], 0, s[34:35]
	s_waitcnt vmcnt(11)
	v_lshlrev_b32_e32 v74, 16, v196
	v_and_b32_e32 v75, 0xffff0000, v196
	v_lshlrev_b32_e32 v66, 16, v197
	v_and_b32_e32 v67, 0xffff0000, v197
	v_lshlrev_b32_e32 v76, 16, v198
	v_and_b32_e32 v77, 0xffff0000, v198
	v_lshlrev_b32_e32 v68, 16, v199
	v_and_b32_e32 v69, 0xffff0000, v199
	v_pk_mul_f32 v[64:65], v[64:65], v[66:67]
	v_pk_mul_f32 v[62:63], v[62:63], v[74:75]
	v_pk_mul_f32 v[66:67], v[60:61], v[68:69]
	v_pk_mul_f32 v[60:61], v[58:59], v[76:77]
	v_cvt_pk_bf16_f32 v58, v62, v63
	v_cvt_pk_bf16_f32 v59, v64, v65
	v_cvt_pk_bf16_f32 v60, v60, v61
	v_cvt_pk_bf16_f32 v61, v66, v67
	global_store_dwordx4 v[70:71], v[58:61], off

	v_add_u32_e32 v62, 0x90, v132
	v_mad_i64_i32 v[64:65], s[0:1], v62, s47, v[134:135]
	v_lshl_add_u64 v[64:65], v[64:65], 0, v[130:131]
	v_add_co_u32_e32 v66, vcc, s72, v64
	v_ashrrev_i32_e32 v63, 31, v62
	s_nop 0
	v_addc_co_u32_e32 v67, vcc, 0, v65, vcc
	s_waitcnt vmcnt(11)
	v_lshlrev_b32_e32 v68, 16, v200
	v_and_b32_e32 v69, 0xffff0000, v200
	v_lshlrev_b32_e32 v58, 16, v201
	v_and_b32_e32 v59, 0xffff0000, v201
	v_lshlrev_b32_e32 v72, 16, v202
	v_and_b32_e32 v73, 0xffff0000, v202
	v_lshlrev_b32_e32 v60, 16, v203
	v_and_b32_e32 v61, 0xffff0000, v203
	v_pk_mul_f32 v[56:57], v[56:57], v[58:59]
	v_pk_mul_f32 v[54:55], v[54:55], v[68:69]
	v_pk_mul_f32 v[58:59], v[52:53], v[60:61]
	v_pk_mul_f32 v[52:53], v[50:51], v[72:73]
	v_cvt_pk_bf16_f32 v50, v54, v55
	v_cvt_pk_bf16_f32 v51, v56, v57
	v_cvt_pk_bf16_f32 v52, v52, v53
	v_cvt_pk_bf16_f32 v53, v58, v59
	global_store_dwordx4 v[70:71], v[50:53], off offset:256

	v_lshlrev_b64 v[54:55], 12, v[62:63]
	v_lshl_add_u64 v[54:55], s[28:29], 0, v[54:55]
	v_lshl_add_u64 v[54:55], v[54:55], 0, v[130:131]
	v_lshl_add_u64 v[56:57], v[64:65], 0, s[34:35]
	s_waitcnt vmcnt(11)
	v_lshlrev_b32_e32 v58, 16, v216
	v_and_b32_e32 v59, 0xffff0000, v216
	v_lshlrev_b32_e32 v50, 16, v217
	v_and_b32_e32 v51, 0xffff0000, v217
	v_lshlrev_b32_e32 v60, 16, v218
	v_and_b32_e32 v61, 0xffff0000, v218
	v_lshlrev_b32_e32 v52, 16, v219
	v_and_b32_e32 v53, 0xffff0000, v219
	v_pk_mul_f32 v[48:49], v[48:49], v[50:51]
	v_pk_mul_f32 v[46:47], v[46:47], v[58:59]
	v_pk_mul_f32 v[50:51], v[44:45], v[52:53]
	v_pk_mul_f32 v[44:45], v[42:43], v[60:61]
	v_cvt_pk_bf16_f32 v42, v46, v47
	v_cvt_pk_bf16_f32 v43, v48, v49
	v_cvt_pk_bf16_f32 v44, v44, v45
	v_cvt_pk_bf16_f32 v45, v50, v51
	global_store_dwordx4 v[54:55], v[42:45], off

	v_add_u32_e32 v46, 0xa0, v132
	v_mad_i64_i32 v[48:49], s[0:1], v46, s47, v[134:135]
	v_lshl_add_u64 v[48:49], v[48:49], 0, v[130:131]
	v_add_co_u32_e32 v50, vcc, s72, v48
	v_ashrrev_i32_e32 v47, 31, v46
	s_nop 0
	v_addc_co_u32_e32 v51, vcc, 0, v49, vcc
	s_waitcnt vmcnt(11)
	v_lshlrev_b32_e32 v52, 16, v220
	v_and_b32_e32 v53, 0xffff0000, v220
	v_lshlrev_b32_e32 v42, 16, v221
	v_and_b32_e32 v43, 0xffff0000, v221
	v_lshlrev_b32_e32 v56, 16, v222
	v_and_b32_e32 v57, 0xffff0000, v222
	v_lshlrev_b32_e32 v44, 16, v223
	v_and_b32_e32 v45, 0xffff0000, v223
	v_pk_mul_f32 v[40:41], v[40:41], v[42:43]
	v_pk_mul_f32 v[38:39], v[38:39], v[52:53]
	v_pk_mul_f32 v[42:43], v[36:37], v[44:45]
	v_pk_mul_f32 v[36:37], v[34:35], v[56:57]
	v_cvt_pk_bf16_f32 v34, v38, v39
	v_cvt_pk_bf16_f32 v35, v40, v41
	v_cvt_pk_bf16_f32 v36, v36, v37
	v_cvt_pk_bf16_f32 v37, v42, v43
	global_store_dwordx4 v[54:55], v[34:37], off offset:256
	global_load_dwordx4 v[34:37], v[50:51], off
	v_lshlrev_b64 v[38:39], 12, v[46:47]
	v_lshl_add_u64 v[38:39], s[28:29], 0, v[38:39]
	v_lshl_add_u64 v[38:39], v[38:39], 0, v[130:131]
	v_lshl_add_u64 v[40:41], v[48:49], 0, s[34:35]
	s_waitcnt vmcnt(0)
	v_lshlrev_b32_e32 v42, 16, v34
	v_and_b32_e32 v43, 0xffff0000, v34
	v_lshlrev_b32_e32 v34, 16, v35
	v_and_b32_e32 v35, 0xffff0000, v35
	v_lshlrev_b32_e32 v44, 16, v36
	v_and_b32_e32 v45, 0xffff0000, v36
	v_lshlrev_b32_e32 v36, 16, v37
	v_and_b32_e32 v37, 0xffff0000, v37
	v_pk_mul_f32 v[32:33], v[32:33], v[34:35]
	v_pk_mul_f32 v[30:31], v[30:31], v[42:43]
	v_pk_mul_f32 v[34:35], v[28:29], v[36:37]
	v_pk_mul_f32 v[28:29], v[26:27], v[44:45]
	v_cvt_pk_bf16_f32 v26, v30, v31
	v_cvt_pk_bf16_f32 v27, v32, v33
	v_cvt_pk_bf16_f32 v28, v28, v29
	v_cvt_pk_bf16_f32 v29, v34, v35
	global_store_dwordx4 v[38:39], v[26:29], off
	global_load_dwordx4 v[26:29], v[40:41], off offset:256
	v_add_u32_e32 v30, 0xb0, v132
	v_mad_i64_i32 v[32:33], s[0:1], v30, s47, v[134:135]
	v_lshl_add_u64 v[32:33], v[32:33], 0, v[130:131]
	v_add_co_u32_e32 v34, vcc, s72, v32
	v_ashrrev_i32_e32 v31, 31, v30
	s_nop 0
	v_addc_co_u32_e32 v35, vcc, 0, v33, vcc
	s_and_b64 vcc, exec, s[36:37]
	s_waitcnt vmcnt(0)
	v_lshlrev_b32_e32 v36, 16, v26
	v_and_b32_e32 v37, 0xffff0000, v26
	v_lshlrev_b32_e32 v26, 16, v27
	v_and_b32_e32 v27, 0xffff0000, v27
	v_lshlrev_b32_e32 v40, 16, v28
	v_and_b32_e32 v41, 0xffff0000, v28
	v_lshlrev_b32_e32 v28, 16, v29
	v_and_b32_e32 v29, 0xffff0000, v29
	v_pk_mul_f32 v[24:25], v[24:25], v[26:27]
	v_pk_mul_f32 v[22:23], v[22:23], v[36:37]
	v_pk_mul_f32 v[26:27], v[20:21], v[28:29]
	v_pk_mul_f32 v[20:21], v[18:19], v[40:41]
	v_cvt_pk_bf16_f32 v18, v22, v23
	v_cvt_pk_bf16_f32 v19, v24, v25
	v_cvt_pk_bf16_f32 v20, v20, v21
	v_cvt_pk_bf16_f32 v21, v26, v27
	global_store_dwordx4 v[38:39], v[18:21], off offset:256
	global_load_dwordx4 v[18:21], v[34:35], off
	v_lshlrev_b64 v[22:23], 12, v[30:31]
	v_lshl_add_u64 v[22:23], s[28:29], 0, v[22:23]
	v_lshl_add_u64 v[22:23], v[22:23], 0, v[130:131]
	v_lshl_add_u64 v[24:25], v[32:33], 0, s[34:35]
	s_waitcnt vmcnt(0)
	v_lshlrev_b32_e32 v26, 16, v18
	v_and_b32_e32 v27, 0xffff0000, v18
	v_lshlrev_b32_e32 v18, 16, v19
	v_and_b32_e32 v19, 0xffff0000, v19
	v_lshlrev_b32_e32 v28, 16, v20
	v_and_b32_e32 v29, 0xffff0000, v20
	v_lshlrev_b32_e32 v20, 16, v21
	v_and_b32_e32 v21, 0xffff0000, v21
	v_pk_mul_f32 v[16:17], v[16:17], v[18:19]
	v_pk_mul_f32 v[14:15], v[14:15], v[26:27]
	v_pk_mul_f32 v[18:19], v[12:13], v[20:21]
	v_pk_mul_f32 v[12:13], v[10:11], v[28:29]
	v_cvt_pk_bf16_f32 v10, v14, v15
	v_cvt_pk_bf16_f32 v11, v16, v17
	v_cvt_pk_bf16_f32 v12, v12, v13
	v_cvt_pk_bf16_f32 v13, v18, v19
	global_store_dwordx4 v[22:23], v[10:13], off
	global_load_dwordx4 v[10:13], v[24:25], off offset:256
	s_waitcnt vmcnt(0)
	v_lshlrev_b32_e32 v14, 16, v10
	v_and_b32_e32 v15, 0xffff0000, v10
	v_lshlrev_b32_e32 v10, 16, v11
	v_and_b32_e32 v11, 0xffff0000, v11
	v_lshlrev_b32_e32 v16, 16, v12
	v_and_b32_e32 v17, 0xffff0000, v12
	v_lshlrev_b32_e32 v12, 16, v13
	v_and_b32_e32 v13, 0xffff0000, v13
	v_pk_mul_f32 v[8:9], v[8:9], v[10:11]
	v_pk_mul_f32 v[6:7], v[6:7], v[14:15]
	v_pk_mul_f32 v[10:11], v[4:5], v[12:13]
	v_pk_mul_f32 v[4:5], v[2:3], v[16:17]
	v_cvt_pk_bf16_f32 v2, v6, v7
	v_cvt_pk_bf16_f32 v3, v8, v9
	v_cvt_pk_bf16_f32 v4, v4, v5
	v_cvt_pk_bf16_f32 v5, v10, v11
	global_store_dwordx4 v[22:23], v[2:5], off offset:256
	s_cbranch_vccz .LBB0_715
	s_waitcnt vmcnt(0)
	s_cmpk_gt_u32 s97, 0xff
	s_cbranch_scc1 .LBB0_732
	s_barrier
